# FFN-up tile loop: next-tile index arithmetic moved behind the peeled iteration's LDS reads and DMA issue
# baseline (speedup 1.0000x reference)
; #define PG8_WAIT_V(n) asm volatile("s_waitcnt vmcnt(" #n ")" ::: "memory")
;     __host__ __device__ bool next(int i, Unit& u) const {
;         const long L = (long)i * G + c; if (L >= nwg) return false;
;         int wgid = (int)L; { const int q = nwg / NXCD, r = nwg % NXCD, xcd = wgid % NXCD, off = wgid / NXCD; wgid = (xcd < r ? xcd * (q + 1) : r * (q + 1) + (xcd - r) * q) + off; }
;         const int nig = WGM * nN, gid = wgid / nig, fm = gid * WGM, gsz = (nM - fm) < WGM ? (nM - fm) : WGM;
;         u.pm = fm + ((wgid % nig) % gsz); u.pn = (wgid % nig) / gsz; return true;
;     }
; template <class Epi, class Sched, bool ALIGN_EPI = false, bool SP2 = false>
; __device__ __forceinline__ void gemm_phase(PG8_LAS unsigned char* lds, const Gemm g, const Sched& S, const Epi& E, const int tid_) {
;     ...
;         const bool has_next = S.next(ui + 1, nxt);
;         const char* nA = has_next ? (const char*)g.A + (size_t)nxt.pm * tstep : cA; const char* nB = has_next ? (const char*)g.Bt + (size_t)nxt.pn * tstep : cB;
;         for (int t = 0; t < nt; t += 2) {
;             const bool last = (t == nt - 2);
;             const char* a1 = cA + (size_t)(t + 1) * kstep;
;             const char* a2 = last ? nA : cA + (size_t)(t + 2) * kstep; const char* b2 = last ? nB : cB + (size_t)(t + 2) * kstep;
;             const char* a3 = a2 + kstep; const char* b3 = b2 + kstep;
;             if (last && has_next) S.a_ready(nxt);
;             if constexpr (SP2) {
;             PG8_LDB(B0, 0, 0); PG8_LDB(B1, 0, 1); PG8_SCHED; PG8_LDA(At, 0, 0); PG8_STAGE(PG8_SA(1, 1), a1 + hstep, voffA);
;             PG8_WAIT_V(8); PG8_WAIT_L(0); PG8_BAR; PG8_MMA(0, 0, At, B0); PG8_MMA(0, 1, At, B1); PG8_BAR; PG8_SCHED;
;             PG8_LDA(At, 0, 1); PG8_STAGE(PG8_SB(0, 0), b2, voffB); PG8_STAGE(PG8_SB(0, 1), b2 + hstepB, voffB); PG8_STAGE(PG8_SA(0, 0), a2, voffA);
;             PG8_WAIT_V(8); PG8_WAIT_L(0); PG8_BAR; PG8_MMA(1, 0, At, B0); PG8_MMA(1, 1, At, B1); PG8_BAR; PG8_SCHED;
;             PG8_LDB(B0, 1, 0); PG8_LDB(B1, 1, 1); PG8_SCHED; PG8_LDA(At, 1, 0); PG8_STAGE(PG8_SA(0, 1), a2 + hstep, voffA);
;             PG8_WAIT_V(8); PG8_WAIT_L(0); PG8_BAR; PG8_MMA(0, 0, At, B0); PG8_MMA(0, 1, At, B1); PG8_BAR; PG8_SCHED;
;             PG8_LDA(At, 1, 1); PG8_STAGE(PG8_SB(1, 0), b3, voffB); PG8_STAGE(PG8_SB(1, 1), b3 + hstepB, voffB); PG8_STAGE(PG8_SA(1, 0), a3, voffA);
.LBB0_21:
.LBB0_23:
	s_add_u32 s24, s24, 0x40080
	s_addc_u32 s25, s25, 0
	s_add_u32 s55, s26, 0x100
	s_addc_u32 s56, s27, 0
	s_mov_b32 s57, -2
	v_add_u32_e32 v154, s23, v163
	v_add_u32_e32 v174, s37, v163
	ds_read_b128 v[132:135], v154
	ds_read_b128 v[146:149], v154 offset:1024
	ds_read_b128 v[150:153], v154 offset:2048
	ds_read_b128 v[154:157], v154 offset:3072
	ds_read_b128 v[158:161], v174
	ds_read_b128 v[166:169], v174 offset:1024
	ds_read_b128 v[170:173], v174 offset:2048
	ds_read_b128 v[174:177], v174 offset:3072
	s_add_u32 s26, s24, 0xfffc0080
	s_addc_u32 s27, s25, -1
	s_cmp_eq_u32 s57, 12
	s_cselect_b32 s29, s2, s27
	s_cselect_b32 s28, s3, s26
	s_cselect_b32 s27, s15, s56
	s_cselect_b32 s26, s17, s55
	v_lshl_add_u64 v[178:179], s[24:25], 0, v[142:143]
	s_add_i32 m0, s40, 0xc000
	ds_read_b128 v[188:191], v165
	ds_read_b128 v[192:195], v165 offset:1024
	ds_read_b128 v[196:199], v165 offset:2048
	ds_read_b128 v[200:203], v165 offset:3072
	ds_read_b128 v[204:207], v165 offset:4096
	ds_read_b128 v[208:211], v165 offset:5120
	ds_read_b128 v[212:215], v165 offset:6144
	ds_read_b128 v[216:219], v165 offset:7168
	global_load_lds_dwordx4 v[178:179], off
	v_lshl_add_u64 v[178:179], s[24:25], 0, v[144:145]
	s_add_i32 m0, s40, 0xe000
	s_nop 0
	global_load_lds_dwordx4 v[178:179], off
	s_add_i32 s53, s53, 1
	s_mul_i32 s2, s53, s52
	s_mul_hi_u32 s3, s53, s90
	s_add_i32 s3, s3, s2
	s_mul_i32 s2, s53, s90
	s_add_u32 s2, s2, s91
	s_addc_u32 s3, s3, s34
	v_mov_b64_e32 v[4:5], 0x1600
	v_cmp_lt_i64_e64 s[6:7], s[2:3], v[4:5]
	v_mov_b64_e32 v[4:5], 0x15ff
	v_cmp_gt_i64_e32 vcc, s[2:3], v[4:5]
	s_cbranch_vccnz .Lnt_23
	s_ashr_i32 s3, s2, 31
	s_lshr_b32 s3, s3, 29
	s_add_i32 s3, s2, s3
	s_ashr_i32 s14, s3, 3
	s_and_b32 s3, s3, -8
	s_sub_i32 s2, s2, s3
	s_cmp_lt_i32 s2, 0
	s_cselect_b32 s3, s71, 0x2c0
	s_mul_i32 s2, s2, s3
	s_add_i32 s2, s2, s14
	s_mul_hi_i32 s3, s2, 0x2e8ba2e9
	s_lshr_b32 s14, s3, 31
	s_ashr_i32 s3, s3, 5
	s_add_i32 s3, s3, s14
	s_lshl_b32 s15, s3, 3
	s_sub_i32 s14, 0x100, s15
	s_min_i32 s16, s14, 8
	s_abs_i32 s14, s16
	v_cvt_f32_u32_e32 v4, s14
	s_sub_i32 s18, 0, s14
	s_mulk_i32 s3, 0xb0
	s_sub_i32 s2, s2, s3
	v_rcp_iflag_f32_e32 v4, v4
	s_abs_i32 s3, s2
	s_xor_b32 s17, s2, s16
	s_ashr_i32 s17, s17, 31
	v_mul_f32_e32 v4, 0x4f7ffffe, v4
	v_cvt_u32_f32_e32 v4, v4
	s_nop 0
	v_readfirstlane_b32 s19, v4
	s_mul_i32 s18, s18, s19
	s_mul_hi_u32 s18, s19, s18
	s_add_i32 s19, s19, s18
	s_mul_hi_u32 s18, s3, s19
	s_mul_i32 s19, s18, s14
	s_sub_i32 s3, s3, s19
	s_add_i32 s20, s18, 1
	s_sub_i32 s19, s3, s14
	s_cmp_ge_u32 s3, s14
	s_cselect_b32 s18, s20, s18
	s_cselect_b32 s3, s19, s3
	s_add_i32 s19, s18, 1
	s_cmp_ge_u32 s3, s14
	s_cselect_b32 s3, s19, s18
	s_xor_b32 s3, s3, s17
	s_sub_i32 s14, s3, s17
	s_mul_i32 s3, s14, s16
	s_sub_i32 s2, s2, s3
	s_add_i32 s16, s15, s2
.Lnt_23:
	s_ashr_i32 s17, s16, 31
	s_lshl_b64 s[2:3], s[16:17], 19
	s_add_u32 s18, s78, s2
	s_addc_u32 s19, s79, s3
	s_and_b64 s[2:3], s[6:7], exec
	s_cselect_b32 s2, s19, s25
	s_cselect_b32 s3, s18, s24
	s_ashr_i32 s15, s14, 31
	s_lshl_b64 s[20:21], s[14:15], 19
	s_add_u32 s20, s30, s20
	s_addc_u32 s21, s31, s21
	s_and_b64 vcc, s[6:7], exec
	s_cselect_b32 s15, s21, s27
	s_cselect_b32 s17, s20, s26
	s_cmp_lg_u32 s53, 1
	s_cbranch_scc1 .Lpeel1_w1
	s_waitcnt vmcnt(8)
